# attention fast path: waves 4-7 start each key tile's matrix work 256 cycles after their SIMD partners (s_sleep 4), so that one wave's MFMA phase runs beside the other's VALU phase
# baseline (speedup 1.0000x reference)
.LBB0_873:
	s_cmpk_eq_i32 s71, 0xffd0
	s_cselect_b64 s[34:35], -1, 0
	s_and_b64 s[4:5], s[34:35], exec
	s_cselect_b32 s84, 0, s71
	s_cmp_gt_i32 s84, s29
	s_cselect_b64 s[4:5], -1, 0
	s_or_b64 s[4:5], s[58:59], s[4:5]
	s_and_b64 vcc, exec, s[4:5]
	s_cbranch_vccnz .LBB0_883
	s_add_i32 s4, s84, 63
	s_cmp_gt_i32 s4, s95
	s_cselect_b64 s[4:5], -1, 0
	s_or_b64 s[4:5], s[34:35], s[4:5]
	s_and_b64 vcc, exec, s[4:5]
	s_cbranch_vccnz .Lattn_orig
	ds_read_b128 v[88:91], v221
	ds_read_b128 v[92:95], v221 offset:64
	ds_read_b128 v[164:167], v221 offset:576
	ds_read_b128 v[168:171], v221 offset:640
	ds_read_b128 v[172:175], v221 offset:4608
	ds_read_b128 v[236:239], v221 offset:4672
	ds_read_b128 v[240:243], v221 offset:5184
	ds_read_b128 v[160:163], v221 offset:5248
	s_cmp_lt_u32 s30, 4
	s_cbranch_scc1 .Lattn_nostag
	s_sleep 4
.Lattn_nostag:
	v_readlane_b32 s4, v84, 0
	v_readlane_b32 s5, v75, 63
	v_pk_add_f32 v[116:117], v[140:141], v[84:85] neg_lo:[0,1] neg_hi:[0,1]
	v_pk_add_f32 v[118:119], v[140:141], v[86:87] neg_lo:[0,1] neg_hi:[0,1]
	v_pk_add_f32 v[100:101], v[142:143], v[84:85] neg_lo:[0,1] neg_hi:[0,1]
	v_pk_add_f32 v[102:103], v[142:143], v[86:87] neg_lo:[0,1] neg_hi:[0,1]
	v_pk_add_f32 v[112:113], v[140:141], v[76:77] neg_lo:[0,1] neg_hi:[0,1]
	v_pk_add_f32 v[114:115], v[140:141], v[78:79] neg_lo:[0,1] neg_hi:[0,1]
	v_pk_add_f32 v[96:97], v[142:143], v[76:77] neg_lo:[0,1] neg_hi:[0,1]
	v_pk_add_f32 v[98:99], v[142:143], v[78:79] neg_lo:[0,1] neg_hi:[0,1]
	v_pk_add_f32 v[108:109], v[140:141], v[80:81] neg_lo:[0,1] neg_hi:[0,1]
	v_pk_add_f32 v[110:111], v[140:141], v[82:83] neg_lo:[0,1] neg_hi:[0,1]
	v_pk_add_f32 v[244:245], v[142:143], v[80:81] neg_lo:[0,1] neg_hi:[0,1]
	v_pk_add_f32 v[246:247], v[142:143], v[82:83] neg_lo:[0,1] neg_hi:[0,1]
	v_pk_add_f32 v[104:105], v[140:141], v[72:73] neg_lo:[0,1] neg_hi:[0,1]
	v_pk_add_f32 v[106:107], v[140:141], v[74:75] neg_lo:[0,1] neg_hi:[0,1]
	v_pk_add_f32 v[248:249], v[142:143], v[72:73] neg_lo:[0,1] neg_hi:[0,1]
	v_pk_add_f32 v[250:251], v[142:143], v[74:75] neg_lo:[0,1] neg_hi:[0,1]
	v_mov_b32_e32 v234, s5
	v_sub_f32_e32 v234, s4, v234
	v_add_f32_e32 v231, v227, v234
	v_add_f32_e32 v230, v226, v234
	v_exp_f32_e64 v232, -v234
	v_pk_add_f32 v[116:117], v[116:117], v[230:231] op_sel:[0,1] op_sel_hi:[1,1] neg_lo:[0,1] neg_hi:[0,1]
	v_pk_add_f32 v[118:119], v[118:119], v[230:231] op_sel:[0,1] op_sel_hi:[1,1] neg_lo:[0,1] neg_hi:[0,1]
	v_pk_add_f32 v[100:101], v[100:101], v[230:231] op_sel_hi:[1,0] neg_lo:[0,1] neg_hi:[0,1]
	v_pk_add_f32 v[102:103], v[102:103], v[230:231] op_sel_hi:[1,0] neg_lo:[0,1] neg_hi:[0,1]
	v_pk_add_f32 v[112:113], v[112:113], v[230:231] op_sel:[0,1] op_sel_hi:[1,1] neg_lo:[0,1] neg_hi:[0,1]
	v_pk_add_f32 v[114:115], v[114:115], v[230:231] op_sel:[0,1] op_sel_hi:[1,1] neg_lo:[0,1] neg_hi:[0,1]
	v_pk_add_f32 v[96:97], v[96:97], v[230:231] op_sel_hi:[1,0] neg_lo:[0,1] neg_hi:[0,1]
	v_pk_add_f32 v[98:99], v[98:99], v[230:231] op_sel_hi:[1,0] neg_lo:[0,1] neg_hi:[0,1]
	v_pk_add_f32 v[108:109], v[108:109], v[230:231] op_sel:[0,1] op_sel_hi:[1,1] neg_lo:[0,1] neg_hi:[0,1]
	v_pk_add_f32 v[110:111], v[110:111], v[230:231] op_sel:[0,1] op_sel_hi:[1,1] neg_lo:[0,1] neg_hi:[0,1]
	v_pk_add_f32 v[244:245], v[244:245], v[230:231] op_sel_hi:[1,0] neg_lo:[0,1] neg_hi:[0,1]
	v_pk_add_f32 v[246:247], v[246:247], v[230:231] op_sel_hi:[1,0] neg_lo:[0,1] neg_hi:[0,1]
	v_pk_add_f32 v[104:105], v[104:105], v[230:231] op_sel:[0,1] op_sel_hi:[1,1] neg_lo:[0,1] neg_hi:[0,1]
	v_pk_add_f32 v[106:107], v[106:107], v[230:231] op_sel:[0,1] op_sel_hi:[1,1] neg_lo:[0,1] neg_hi:[0,1]
	v_pk_add_f32 v[248:249], v[248:249], v[230:231] op_sel_hi:[1,0] neg_lo:[0,1] neg_hi:[0,1]
	v_pk_add_f32 v[250:251], v[250:251], v[230:231] op_sel_hi:[1,0] neg_lo:[0,1] neg_hi:[0,1]
	s_waitcnt lgkmcnt(4)
	v_mfma_f32_16x16x32_bf16 v[116:119], v[88:91], v[0:3], v[116:119]
	v_mfma_f32_16x16x32_bf16 v[100:103], v[88:91], v[8:11], v[100:103]
	v_mfma_f32_16x16x32_bf16 v[112:115], v[164:167], v[0:3], v[112:115]
	v_mfma_f32_16x16x32_bf16 v[96:99], v[164:167], v[8:11], v[96:99]
	v_mfma_f32_16x16x32_bf16 v[116:119], v[92:95], v[4:7], v[116:119]
	v_mfma_f32_16x16x32_bf16 v[100:103], v[92:95], v[12:15], v[100:103]
	v_mfma_f32_16x16x32_bf16 v[112:115], v[168:171], v[4:7], v[112:115]
	v_mfma_f32_16x16x32_bf16 v[96:99], v[168:171], v[12:15], v[96:99]
	s_waitcnt lgkmcnt(0)
	v_mfma_f32_16x16x32_bf16 v[108:111], v[172:175], v[0:3], v[108:111]
	v_mfma_f32_16x16x32_bf16 v[244:247], v[172:175], v[8:11], v[244:247]
	v_mfma_f32_16x16x32_bf16 v[104:107], v[240:243], v[0:3], v[104:107]
	v_mfma_f32_16x16x32_bf16 v[248:251], v[240:243], v[8:11], v[248:251]
	v_mfma_f32_16x16x32_bf16 v[108:111], v[236:239], v[4:7], v[108:111]
	v_mfma_f32_16x16x32_bf16 v[244:247], v[236:239], v[12:15], v[244:247]
	v_mfma_f32_16x16x32_bf16 v[104:107], v[160:163], v[4:7], v[104:107]
	v_mfma_f32_16x16x32_bf16 v[248:251], v[160:163], v[12:15], v[248:251]
	ds_read_b128 v[88:91], v222 offset:9216
	ds_read_b128 v[92:95], v222 offset:9280
	ds_read_b128 v[164:167], v222 offset:11520
	ds_read_b128 v[168:171], v222 offset:11584
	ds_read_b128 v[172:175], v222 offset:13824
	ds_read_b128 v[236:239], v222 offset:13888
	ds_read_b128 v[240:243], v223 offset:9216
	ds_read_b128 v[160:163], v223 offset:9280
	v_max3_f32 v228, v116, v117, v118
	v_max3_f32 v229, v100, v101, v102
	v_max3_f32 v228, v228, v119, v112
	v_max3_f32 v229, v229, v103, v96
	v_max3_f32 v228, v228, v113, v114
	v_max3_f32 v229, v229, v97, v98
	v_max3_f32 v228, v228, v115, v108
	v_max3_f32 v229, v229, v99, v244
	v_max3_f32 v228, v228, v109, v110
	v_max3_f32 v229, v229, v245, v246
	v_max3_f32 v228, v228, v111, v104
	v_max3_f32 v229, v229, v247, v248
	v_max3_f32 v228, v228, v105, v106
	v_max3_f32 v229, v229, v249, v250
	v_max_f32_e32 v228, v228, v107
	v_max_f32_e32 v229, v229, v251
	v_max_f32_e32 v202, v228, v229
	v_cmp_lt_f32_e32 vcc, 0x42800000, v202
	s_cbranch_vccnz .Lattn_orig
	v_mov_b32_e32 v226, v230
	v_mov_b32_e32 v227, v231
	v_pk_mul_f32 v[52:53], v[52:53], v[232:233] op_sel_hi:[1,0]
	v_pk_mul_f32 v[54:55], v[54:55], v[232:233] op_sel_hi:[1,0]
	v_pk_mul_f32 v[44:45], v[44:45], v[232:233] op_sel_hi:[1,0]
	v_pk_mul_f32 v[46:47], v[46:47], v[232:233] op_sel_hi:[1,0]
	v_pk_mul_f32 v[40:41], v[40:41], v[232:233] op_sel_hi:[1,0]
	v_pk_mul_f32 v[42:43], v[42:43], v[232:233] op_sel_hi:[1,0]
	v_pk_mul_f32 v[48:49], v[48:49], v[232:233] op_sel_hi:[1,0]
	v_pk_mul_f32 v[50:51], v[50:51], v[232:233] op_sel_hi:[1,0]
	v_pk_mul_f32 v[36:37], v[36:37], v[232:233] op_sel_hi:[1,0]
	v_pk_mul_f32 v[38:39], v[38:39], v[232:233] op_sel_hi:[1,0]
	v_pk_mul_f32 v[28:29], v[28:29], v[232:233] op_sel_hi:[1,0]
	v_pk_mul_f32 v[30:31], v[30:31], v[232:233] op_sel_hi:[1,0]
	v_pk_mul_f32 v[16:17], v[16:17], v[232:233] op_sel_hi:[1,0]
	v_pk_mul_f32 v[18:19], v[18:19], v[232:233] op_sel_hi:[1,0]
	v_pk_mul_f32 v[32:33], v[32:33], v[232:233] op_sel_hi:[1,0]
	v_pk_mul_f32 v[34:35], v[34:35], v[232:233] op_sel_hi:[1,0]
	v_exp_f32_e32 v116, v116
	v_exp_f32_e32 v117, v117
	v_exp_f32_e32 v118, v118
	v_exp_f32_e32 v119, v119
	v_exp_f32_e32 v112, v112
	v_exp_f32_e32 v113, v113
	v_exp_f32_e32 v114, v114
	v_exp_f32_e32 v115, v115
	v_exp_f32_e32 v108, v108
	v_exp_f32_e32 v109, v109
	v_exp_f32_e32 v110, v110
	v_exp_f32_e32 v111, v111
	v_exp_f32_e32 v104, v104
	v_exp_f32_e32 v105, v105
	v_exp_f32_e32 v106, v106
	v_exp_f32_e32 v107, v107
	v_exp_f32_e32 v100, v100
	v_exp_f32_e32 v101, v101
	v_exp_f32_e32 v102, v102
	v_exp_f32_e32 v103, v103
	v_exp_f32_e32 v96, v96
	v_exp_f32_e32 v97, v97
	v_exp_f32_e32 v98, v98
	v_exp_f32_e32 v99, v99
	v_exp_f32_e32 v244, v244
	v_exp_f32_e32 v245, v245
	v_exp_f32_e32 v246, v246
	v_exp_f32_e32 v247, v247
	v_exp_f32_e32 v248, v248
	v_exp_f32_e32 v249, v249
	v_exp_f32_e32 v250, v250
	v_exp_f32_e32 v251, v251
	v_add_f32_e32 v228, 0, v116
	v_add_f32_e32 v229, 0, v100
	v_add_f32_e32 v228, v117, v228
	v_add_f32_e32 v229, v101, v229
	v_add_f32_e32 v228, v118, v228
	v_add_f32_e32 v229, v102, v229
	v_add_f32_e32 v228, v119, v228
	v_add_f32_e32 v229, v103, v229
	v_add_f32_e32 v228, v112, v228
	v_add_f32_e32 v229, v96, v229
	v_add_f32_e32 v228, v113, v228
	v_add_f32_e32 v229, v97, v229
	v_add_f32_e32 v228, v114, v228
	v_add_f32_e32 v229, v98, v229
	v_add_f32_e32 v228, v115, v228
	v_add_f32_e32 v229, v99, v229
	v_add_f32_e32 v228, v108, v228
	v_add_f32_e32 v229, v244, v229
	v_add_f32_e32 v228, v109, v228
	v_add_f32_e32 v229, v245, v229
	v_add_f32_e32 v228, v110, v228
	v_add_f32_e32 v229, v246, v229
	v_add_f32_e32 v228, v111, v228
	v_add_f32_e32 v229, v247, v229
	v_add_f32_e32 v228, v104, v228
	v_add_f32_e32 v229, v248, v229
	v_add_f32_e32 v228, v105, v228
	v_add_f32_e32 v229, v249, v229
	v_add_f32_e32 v228, v106, v228
	v_add_f32_e32 v229, v250, v229
	v_add_f32_e32 v228, v107, v228
	v_add_f32_e32 v229, v251, v229
	v_cvt_pk_bf16_f32 v76, v116, v117
	v_cvt_pk_bf16_f32 v77, v118, v119
	v_cvt_pk_bf16_f32 v78, v112, v113
	v_cvt_pk_bf16_f32 v79, v114, v115
	v_cvt_pk_bf16_f32 v84, v100, v101
	v_cvt_pk_bf16_f32 v85, v102, v103
	v_cvt_pk_bf16_f32 v86, v96, v97
	v_cvt_pk_bf16_f32 v87, v98, v99
	v_cvt_pk_bf16_f32 v72, v108, v109
	v_cvt_pk_bf16_f32 v73, v110, v111
	v_cvt_pk_bf16_f32 v74, v104, v105
	v_cvt_pk_bf16_f32 v75, v106, v107
	v_cvt_pk_bf16_f32 v80, v244, v245
	v_cvt_pk_bf16_f32 v81, v246, v247
	v_cvt_pk_bf16_f32 v82, v248, v249
	v_cvt_pk_bf16_f32 v83, v250, v251
	v_fma_f32 v225, v225, v232, v228
	v_fma_f32 v224, v224, v232, v229
	s_nop 1
	s_waitcnt lgkmcnt(7)
	v_mfma_f32_16x16x32_bf16 v[52:55], v[88:91], v[76:79], v[52:55]
	v_mfma_f32_16x16x32_bf16 v[36:39], v[88:91], v[84:87], v[36:39]
	s_waitcnt lgkmcnt(6)
	v_mfma_f32_16x16x32_bf16 v[52:55], v[92:95], v[72:75], v[52:55]
	v_mfma_f32_16x16x32_bf16 v[36:39], v[92:95], v[80:83], v[36:39]
	s_waitcnt lgkmcnt(5)
	v_mfma_f32_16x16x32_bf16 v[44:47], v[164:167], v[76:79], v[44:47]
	v_mfma_f32_16x16x32_bf16 v[28:31], v[164:167], v[84:87], v[28:31]
	s_waitcnt lgkmcnt(4)
	v_mfma_f32_16x16x32_bf16 v[44:47], v[168:171], v[72:75], v[44:47]
	v_mfma_f32_16x16x32_bf16 v[28:31], v[168:171], v[80:83], v[28:31]
	s_waitcnt lgkmcnt(3)
	v_mfma_f32_16x16x32_bf16 v[40:43], v[172:175], v[76:79], v[40:43]
	v_mfma_f32_16x16x32_bf16 v[16:19], v[172:175], v[84:87], v[16:19]
	s_waitcnt lgkmcnt(2)
	v_mfma_f32_16x16x32_bf16 v[40:43], v[236:239], v[72:75], v[40:43]
	v_mfma_f32_16x16x32_bf16 v[16:19], v[236:239], v[80:83], v[16:19]
	s_waitcnt lgkmcnt(1)
	v_mfma_f32_16x16x32_bf16 v[48:51], v[240:243], v[76:79], v[48:51]
	v_mfma_f32_16x16x32_bf16 v[32:35], v[240:243], v[84:87], v[32:35]
	s_waitcnt lgkmcnt(0)
	v_mfma_f32_16x16x32_bf16 v[48:51], v[160:163], v[72:75], v[48:51]
	v_mfma_f32_16x16x32_bf16 v[32:35], v[160:163], v[80:83], v[32:35]
	s_branch .LBB0_883
